# EpiMlpIn epilogue rewritten by hand (packed f32 math, per-row counted waits); acc zeroing via v_mov_b64; plus v075 stack
# baseline (speedup 1.0000x reference)
; template <class Epi, class Sched, bool ALIGN_EPI = false, bool SP2 = false>
; __device__ __forceinline__ void gemm_phase(PG8_LAS unsigned char* lds, const Gemm g, const Sched& S, const Epi& E) {
;     ...
;         const bool has_next = S.next(ui + 1, nxt);
;         const char* nA = has_next ? (const char*)g.A + (size_t)nxt.pm * tstep : cA; const char* nB = has_next ? (const char*)g.Bt + (size_t)nxt.pn * tstep : cB;
;     ...
; #pragma unroll
;         for (int a = 0; a < 2; ++a)
; #pragma unroll
;             for (int b = 0; b < 2; ++b)
; #pragma unroll
;                 for (int m = 0; m < 4; ++m)
; #pragma unroll
;                     for (int n = 0; n < 2; ++n) acc[a][b][m][n] = (f32x4){0.f, 0.f, 0.f, 0.f};
.LBB0_147:
	s_ashr_i32 s21, s20, 31
	s_lshl_b64 s[24:25], s[20:21], 19
	s_add_u32 s24, s39, s24
	s_addc_u32 s25, s38, s25
	s_and_b64 s[26:27], s[22:23], exec
	s_cselect_b32 s21, s25, s1
	s_cselect_b32 s34, s24, s0
	s_ashr_i32 s19, s18, 31
	s_lshl_b64 s[26:27], s[18:19], 19
	s_add_u32 s26, s48, s26
	s_addc_u32 s27, s50, s27
	s_and_b64 s[30:31], s[22:23], exec
	s_cselect_b32 s19, s27, s29
	s_cselect_b32 s41, s26, s28
	s_add_u32 s30, s0, 0x40080
	s_addc_u32 s31, s1, 0
	s_add_u32 s58, s28, 0x100
	s_addc_u32 s59, s29, 0
	s_mov_b32 s60, -2
	s_mov_b64 vcc, 0
	v_mov_b64_e32 v[0:1], 0
	v_mov_b64_e32 v[2:3], 0
	v_mov_b64_e32 v[4:5], 0
	v_mov_b64_e32 v[6:7], 0
	v_mov_b64_e32 v[8:9], 0
	v_mov_b64_e32 v[10:11], 0
	v_mov_b64_e32 v[12:13], 0
	v_mov_b64_e32 v[14:15], 0
	v_mov_b64_e32 v[16:17], 0
	v_mov_b64_e32 v[18:19], 0
	v_mov_b64_e32 v[20:21], 0
	v_mov_b64_e32 v[22:23], 0
	v_mov_b64_e32 v[24:25], 0
	v_mov_b64_e32 v[26:27], 0
	v_mov_b64_e32 v[28:29], 0
	v_mov_b64_e32 v[30:31], 0
	v_mov_b64_e32 v[32:33], 0
	v_mov_b64_e32 v[34:35], 0
	v_mov_b64_e32 v[36:37], 0
	v_mov_b64_e32 v[38:39], 0
	v_mov_b64_e32 v[40:41], 0
	v_mov_b64_e32 v[42:43], 0
	v_mov_b64_e32 v[44:45], 0
	v_mov_b64_e32 v[46:47], 0
	v_mov_b64_e32 v[48:49], 0
	v_mov_b64_e32 v[50:51], 0
	v_mov_b64_e32 v[52:53], 0
	v_mov_b64_e32 v[54:55], 0
	v_mov_b64_e32 v[56:57], 0
	v_mov_b64_e32 v[58:59], 0
	v_mov_b64_e32 v[60:61], 0
	v_mov_b64_e32 v[62:63], 0
	v_mov_b64_e32 v[64:65], 0
	v_mov_b64_e32 v[66:67], 0
	v_mov_b64_e32 v[68:69], 0
	v_mov_b64_e32 v[70:71], 0
	v_mov_b64_e32 v[72:73], 0
	v_mov_b64_e32 v[74:75], 0
	v_mov_b64_e32 v[76:77], 0
	v_mov_b64_e32 v[78:79], 0
	v_mov_b64_e32 v[80:81], 0
	v_mov_b64_e32 v[82:83], 0
	v_mov_b64_e32 v[84:85], 0
	v_mov_b64_e32 v[86:87], 0
	v_mov_b64_e32 v[88:89], 0
	v_mov_b64_e32 v[90:91], 0
	v_mov_b64_e32 v[92:93], 0
	v_mov_b64_e32 v[94:95], 0
	v_mov_b64_e32 v[96:97], 0
	v_mov_b64_e32 v[98:99], 0
	v_mov_b64_e32 v[100:101], 0
	v_mov_b64_e32 v[102:103], 0
	v_mov_b64_e32 v[104:105], 0
	v_mov_b64_e32 v[106:107], 0
	v_mov_b64_e32 v[108:109], 0
	v_mov_b64_e32 v[110:111], 0
	v_mov_b64_e32 v[112:113], 0
	v_mov_b64_e32 v[114:115], 0
	v_mov_b64_e32 v[116:117], 0
	v_mov_b64_e32 v[118:119], 0
	v_mov_b64_e32 v[120:121], 0
	v_mov_b64_e32 v[122:123], 0
	v_mov_b64_e32 v[124:125], 0
	v_mov_b64_e32 v[126:127], 0
	v_lshl_add_u64 v[128:129], s[30:31], 0, v[140:141]
	v_lshl_add_u64 v[130:131], s[30:31], 0, v[142:143]

; template <class Epi, class Sched, bool ALIGN_EPI = false, bool SP2 = false>
; __device__ __forceinline__ void gemm_phase(PG8_LAS unsigned char* lds, const Gemm g, const Sched& S, const Epi& E) {
;     ...
;         const bool has_next = S.next(ui + 1, nxt);
;         const char* nA = has_next ? (const char*)g.A + (size_t)nxt.pm * tstep : cA; const char* nB = has_next ? (const char*)g.Bt + (size_t)nxt.pn * tstep : cB;
;     ...
; #pragma unroll
;         for (int a = 0; a < 2; ++a)
; #pragma unroll
;             for (int b = 0; b < 2; ++b)
; #pragma unroll
;                 for (int m = 0; m < 4; ++m)
; #pragma unroll
;                     for (int n = 0; n < 2; ++n) acc[a][b][m][n] = (f32x4){0.f, 0.f, 0.f, 0.f};
.LBB0_610:
	s_ashr_i32 s13, s12, 31
	s_lshl_b64 s[16:17], s[12:13], 19
	s_add_u32 s16, s39, s16
	s_addc_u32 s17, s42, s17
	s_and_b64 s[18:19], s[14:15], exec
	s_cselect_b32 s13, s17, s25
	s_cselect_b32 s54, s16, s24
	s_ashr_i32 s11, s10, 31
	s_lshl_b64 s[18:19], s[10:11], 19
	s_add_u32 s18, s43, s18
	s_addc_u32 s19, s44, s19
	s_and_b64 s[30:31], s[14:15], exec
	s_cselect_b32 s11, s19, s29
	s_cselect_b32 s55, s18, s28
	s_add_u32 s30, s24, 0x40080
	s_addc_u32 s31, s25, 0
	s_add_u32 s56, s28, 0x100
	v_lshl_add_u64 v[128:129], s[30:31], 0, v[160:161]
	v_lshl_add_u64 v[130:131], s[30:31], 0, v[162:163]
	s_addc_u32 s57, s29, 0
	s_mov_b32 s58, -2
	s_mov_b64 s[40:41], 0
	v_mov_b64_e32 v[0:1], 0
	v_mov_b64_e32 v[2:3], 0
	v_mov_b64_e32 v[4:5], 0
	v_mov_b64_e32 v[6:7], 0
	v_mov_b64_e32 v[8:9], 0
	v_mov_b64_e32 v[10:11], 0
	v_mov_b64_e32 v[12:13], 0
	v_mov_b64_e32 v[14:15], 0
	v_mov_b64_e32 v[16:17], 0
	v_mov_b64_e32 v[18:19], 0
	v_mov_b64_e32 v[20:21], 0
	v_mov_b64_e32 v[22:23], 0
	v_mov_b64_e32 v[24:25], 0
	v_mov_b64_e32 v[26:27], 0
	v_mov_b64_e32 v[28:29], 0
	v_mov_b64_e32 v[30:31], 0
	v_mov_b64_e32 v[32:33], 0
	v_mov_b64_e32 v[34:35], 0
	v_mov_b64_e32 v[36:37], 0
	v_mov_b64_e32 v[38:39], 0
	v_mov_b64_e32 v[40:41], 0
	v_mov_b64_e32 v[42:43], 0
	v_mov_b64_e32 v[44:45], 0
	v_mov_b64_e32 v[46:47], 0
	v_mov_b64_e32 v[48:49], 0
	v_mov_b64_e32 v[50:51], 0
	v_mov_b64_e32 v[52:53], 0
	v_mov_b64_e32 v[54:55], 0
	v_mov_b64_e32 v[56:57], 0
	v_mov_b64_e32 v[58:59], 0
	v_mov_b64_e32 v[60:61], 0
	v_mov_b64_e32 v[62:63], 0
	v_mov_b64_e32 v[64:65], 0
	v_mov_b64_e32 v[66:67], 0
	v_mov_b64_e32 v[68:69], 0
	v_mov_b64_e32 v[70:71], 0
	v_mov_b64_e32 v[72:73], 0
	v_mov_b64_e32 v[74:75], 0
	v_mov_b64_e32 v[76:77], 0
	v_mov_b64_e32 v[78:79], 0
	v_mov_b64_e32 v[80:81], 0
	v_mov_b64_e32 v[82:83], 0
	v_mov_b64_e32 v[84:85], 0
	v_mov_b64_e32 v[86:87], 0
	v_mov_b64_e32 v[88:89], 0
	v_mov_b64_e32 v[90:91], 0
	v_mov_b64_e32 v[92:93], 0
	v_mov_b64_e32 v[94:95], 0
	v_mov_b64_e32 v[96:97], 0
	v_mov_b64_e32 v[98:99], 0
	v_mov_b64_e32 v[100:101], 0
	v_mov_b64_e32 v[102:103], 0
	v_mov_b64_e32 v[104:105], 0
	v_mov_b64_e32 v[106:107], 0
	v_mov_b64_e32 v[108:109], 0
	v_mov_b64_e32 v[110:111], 0
	v_mov_b64_e32 v[112:113], 0
	v_mov_b64_e32 v[114:115], 0
	v_mov_b64_e32 v[116:117], 0
	v_mov_b64_e32 v[118:119], 0
	v_mov_b64_e32 v[120:121], 0
	v_mov_b64_e32 v[122:123], 0
	v_mov_b64_e32 v[124:125], 0
	v_mov_b64_e32 v[126:127], 0

; __device__ __forceinline__ u32x4 pack8(const f32x4 v0, const f32x4 v1) { u32x4 w; w.x = cvt_pk_bf16(v0[0], v0[1]); w.y = cvt_pk_bf16(v0[2], v0[3]); w.z = cvt_pk_bf16(v1[0], v1[1]); w.w = cvt_pk_bf16(v1[2], v1[3]); return w; }
; __device__ __forceinline__ void row_rs8(float (&rs)[8], const float* ssq, int row0, int fq) {
;     f32x4 p[8];
; #pragma unroll
;     for (int i = 0; i < 8; ++i) p[i] = *(const f32x4*)(ssq + (size_t)(row0 + (i >> 2) * HALF + (i & 3) * 16) * 16 + 4 * fq);
; #pragma unroll
;     for (int i = 0; i < 8; ++i) { float s = (p[i][0] + p[i][1]) + (p[i][2] + p[i][3]); s += __shfl_xor(s, 16); s += __shfl_xor(s, 32); rs[i] = __builtin_amdgcn_rsqf(s * (1.0f / DMODEL) + RMS_EPS); }
;     __device__ __forceinline__ void operator()(const f32x4 (&acc)[2][2][4][2], const Unit& u, int wr, int wc, int fr, int fq) const {
;         const int row0 = u.pm * BM + wr * 64 + fr, col0 = u.pn * BM + wc * 32 + 8 * fq;
;         float rs[8]; row_rs8(rs, ssq, row0, fq);
; #pragma unroll
;         for (int ai = 0; ai < 2; ++ai)
; #pragma unroll
;             for (int m = 0; m < 4; ++m) { const int row = row0 + ai * HALF + m * 16; const float r = rs[ai * 4 + m];
;                 bf16_t* rowp = O + (size_t)row * ldc + col0;
; #pragma unroll
;                 for (int bj = 0; bj < 2; ++bj) { f32x4 v0 = acc[ai][bj][m][0] * r, v1 = acc[ai][bj][m][1] * r;
; #pragma unroll
;                     for (int e = 0; e < 4; ++e) { const float a = fmaxf(v0[e], 0.f), b = fmaxf(v1[e], 0.f); v0[e] = a * a; v1[e] = b * b; }
;                     *(u32x4*)(rowp + bj * HALF) = pack8(v0, v1); } }
.LBB0_614:
	v_readfirstlane_b32 s11, v192
	v_and_b32_e32 v176, 15, v192
	s_lshl_b32 s13, s22, 8
	s_lshr_b32 s22, s11, 8
	s_lshl_b32 s22, s22, 6
	s_add_i32 s22, s22, s13
	v_add_u32_e32 v176, s22, v176
	v_bfe_u32 v177, v192, 4, 2
	s_lshr_b32 s11, s11, 1
	s_and_b32 s11, s11, 0x60
	s_lshl_b32 s13, s20, 8
	s_or_b32 s11, s11, s13
	v_lshl_or_b32 v178, v177, 3, s11
	v_lshlrev_b32_e32 v172, 13, v176
	v_lshl_add_u32 v172, v178, 1, v172
	v_lshlrev_b32_e32 v173, 6, v176
	v_lshl_add_u32 v173, v177, 4, v173
	global_load_dwordx4 v[128:131], v173, s[6:7]
	v_add_u32_e32 v178, 0x400, v173
	global_load_dwordx4 v[132:135], v178, s[6:7]
	v_add_u32_e32 v178, 0x800, v173
	global_load_dwordx4 v[136:139], v178, s[6:7]
	v_add_u32_e32 v178, 0xc00, v173
	global_load_dwordx4 v[140:143], v178, s[6:7]
	v_add_u32_e32 v178, 0x2000, v173
	global_load_dwordx4 v[144:147], v178, s[6:7]
	v_add_u32_e32 v178, 0x2400, v173
	global_load_dwordx4 v[148:151], v178, s[6:7]
	v_add_u32_e32 v178, 0x2800, v173
	global_load_dwordx4 v[164:167], v178, s[6:7]
	v_add_u32_e32 v178, 0x2c00, v173
	global_load_dwordx4 v[168:171], v178, s[6:7]
	v_xor_b32_e32 v174, 16, v241
	v_xor_b32_e32 v175, 32, v241
	v_lshlrev_b32_e32 v174, 2, v174
	v_lshlrev_b32_e32 v175, 2, v175
	s_waitcnt vmcnt(7)
	v_add_f32_e32 v176, v128, v129
	v_add_f32_e32 v177, v130, v131
	v_add_f32_e32 v176, v176, v177
	ds_bpermute_b32 v177, v174, v176
	s_waitcnt lgkmcnt(0)
	v_add_f32_e32 v176, v176, v177
	ds_bpermute_b32 v177, v175, v176
	v_mov_b32_e32 v178, v172
	s_waitcnt lgkmcnt(0)
	v_add_f32_e32 v176, v176, v177
	v_fmamk_f32 v176, v176, 0x3a800000, v193
	v_rsq_f32_e32 v180, v176
	s_nop 0
	v_pk_mul_f32 v[124:125], v[124:125], v[180:181] op_sel_hi:[1,0]
	v_pk_mul_f32 v[126:127], v[126:127], v[180:181] op_sel_hi:[1,0]
	v_pk_mul_f32 v[120:121], v[120:121], v[180:181] op_sel_hi:[1,0]
	v_pk_mul_f32 v[122:123], v[122:123], v[180:181] op_sel_hi:[1,0]
	v_max_f32_e32 v124, 0, v124
	v_max_f32_e32 v125, 0, v125
	v_max_f32_e32 v126, 0, v126
	v_max_f32_e32 v127, 0, v127
	v_max_f32_e32 v120, 0, v120
	v_max_f32_e32 v121, 0, v121
	v_max_f32_e32 v122, 0, v122
	v_max_f32_e32 v123, 0, v123
	v_pk_mul_f32 v[124:125], v[124:125], v[124:125]
	v_pk_mul_f32 v[126:127], v[126:127], v[126:127]
	v_pk_mul_f32 v[120:121], v[120:121], v[120:121]
	v_pk_mul_f32 v[122:123], v[122:123], v[122:123]
	v_cvt_pk_bf16_f32 v124, v124, v125
	v_cvt_pk_bf16_f32 v125, v126, v127
	v_cvt_pk_bf16_f32 v126, v120, v121
	v_cvt_pk_bf16_f32 v127, v122, v123
	global_store_dwordx4 v178, v[124:127], s[0:1]
	v_pk_mul_f32 v[116:117], v[116:117], v[180:181] op_sel_hi:[1,0]
	v_pk_mul_f32 v[118:119], v[118:119], v[180:181] op_sel_hi:[1,0]
	v_pk_mul_f32 v[112:113], v[112:113], v[180:181] op_sel_hi:[1,0]
	v_pk_mul_f32 v[114:115], v[114:115], v[180:181] op_sel_hi:[1,0]
	v_max_f32_e32 v116, 0, v116
	v_max_f32_e32 v117, 0, v117
	v_max_f32_e32 v118, 0, v118
	v_max_f32_e32 v119, 0, v119
	v_max_f32_e32 v112, 0, v112
	v_max_f32_e32 v113, 0, v113
	v_max_f32_e32 v114, 0, v114
	v_max_f32_e32 v115, 0, v115
	v_pk_mul_f32 v[116:117], v[116:117], v[116:117]
	v_pk_mul_f32 v[118:119], v[118:119], v[118:119]
	v_pk_mul_f32 v[112:113], v[112:113], v[112:113]
	v_pk_mul_f32 v[114:115], v[114:115], v[114:115]
	v_cvt_pk_bf16_f32 v116, v116, v117
	v_cvt_pk_bf16_f32 v117, v118, v119
	v_cvt_pk_bf16_f32 v118, v112, v113
	v_cvt_pk_bf16_f32 v119, v114, v115
	global_store_dwordx4 v178, v[116:119], s[0:1] offset:256
	s_waitcnt vmcnt(8)
	v_add_f32_e32 v176, v132, v133
	v_add_f32_e32 v177, v134, v135
	v_add_f32_e32 v176, v176, v177
	ds_bpermute_b32 v177, v174, v176
	s_waitcnt lgkmcnt(0)
	v_add_f32_e32 v176, v176, v177
	ds_bpermute_b32 v177, v175, v176
	v_add_u32_e32 v178, 0x20000, v172
	s_waitcnt lgkmcnt(0)
	v_add_f32_e32 v176, v176, v177
	v_fmamk_f32 v176, v176, 0x3a800000, v193
	v_rsq_f32_e32 v180, v176
	s_nop 0
	v_pk_mul_f32 v[108:109], v[108:109], v[180:181] op_sel_hi:[1,0]
	v_pk_mul_f32 v[110:111], v[110:111], v[180:181] op_sel_hi:[1,0]
	v_pk_mul_f32 v[104:105], v[104:105], v[180:181] op_sel_hi:[1,0]
	v_pk_mul_f32 v[106:107], v[106:107], v[180:181] op_sel_hi:[1,0]
	v_max_f32_e32 v108, 0, v108
	v_max_f32_e32 v109, 0, v109
	v_max_f32_e32 v110, 0, v110
	v_max_f32_e32 v111, 0, v111
	v_max_f32_e32 v104, 0, v104
	v_max_f32_e32 v105, 0, v105
	v_max_f32_e32 v106, 0, v106
	v_max_f32_e32 v107, 0, v107
	v_pk_mul_f32 v[108:109], v[108:109], v[108:109]
	v_pk_mul_f32 v[110:111], v[110:111], v[110:111]
	v_pk_mul_f32 v[104:105], v[104:105], v[104:105]
	v_pk_mul_f32 v[106:107], v[106:107], v[106:107]
	v_cvt_pk_bf16_f32 v108, v108, v109
	v_cvt_pk_bf16_f32 v109, v110, v111
	v_cvt_pk_bf16_f32 v110, v104, v105
	v_cvt_pk_bf16_f32 v111, v106, v107
	global_store_dwordx4 v178, v[108:111], s[0:1]
	v_pk_mul_f32 v[100:101], v[100:101], v[180:181] op_sel_hi:[1,0]
	v_pk_mul_f32 v[102:103], v[102:103], v[180:181] op_sel_hi:[1,0]
	v_pk_mul_f32 v[96:97], v[96:97], v[180:181] op_sel_hi:[1,0]
	v_pk_mul_f32 v[98:99], v[98:99], v[180:181] op_sel_hi:[1,0]
	v_max_f32_e32 v100, 0, v100
	v_max_f32_e32 v101, 0, v101
	v_max_f32_e32 v102, 0, v102
	v_max_f32_e32 v103, 0, v103
	v_max_f32_e32 v96, 0, v96
	v_max_f32_e32 v97, 0, v97
	v_max_f32_e32 v98, 0, v98
	v_max_f32_e32 v99, 0, v99
	v_pk_mul_f32 v[100:101], v[100:101], v[100:101]
	v_pk_mul_f32 v[102:103], v[102:103], v[102:103]
	v_pk_mul_f32 v[96:97], v[96:97], v[96:97]
	v_pk_mul_f32 v[98:99], v[98:99], v[98:99]
	v_cvt_pk_bf16_f32 v100, v100, v101
	v_cvt_pk_bf16_f32 v101, v102, v103
	v_cvt_pk_bf16_f32 v102, v96, v97
	v_cvt_pk_bf16_f32 v103, v98, v99
	global_store_dwordx4 v178, v[100:103], s[0:1] offset:256
	s_waitcnt vmcnt(9)
	v_add_f32_e32 v176, v136, v137
	v_add_f32_e32 v177, v138, v139
	v_add_f32_e32 v176, v176, v177
	ds_bpermute_b32 v177, v174, v176
	s_waitcnt lgkmcnt(0)
; __device__ __forceinline__ u32x4 pack8(const f32x4 v0, const f32x4 v1) { u32x4 w; w.x = cvt_pk_bf16(v0[0], v0[1]); w.y = cvt_pk_bf16(v0[2], v0[3]); w.z = cvt_pk_bf16(v1[0], v1[1]); w.w = cvt_pk_bf16(v1[2], v1[3]); return w; }
; __device__ __forceinline__ void row_rs8(float (&rs)[8], const float* ssq, int row0, int fq) {
;     ...
;     for (int i = 0; i < 8; ++i) { float s = (p[i][0] + p[i][1]) + (p[i][2] + p[i][3]); s += __shfl_xor(s, 16); s += __shfl_xor(s, 32); rs[i] = __builtin_amdgcn_rsqf(s * (1.0f / DMODEL) + RMS_EPS); }
;     __device__ __forceinline__ void operator()(const f32x4 (&acc)[2][2][4][2], const Unit& u, int wr, int wc, int fr, int fq) const {
;     ...
;         for (int ai = 0; ai < 2; ++ai)
; #pragma unroll
;             for (int m = 0; m < 4; ++m) { const int row = row0 + ai * HALF + m * 16; const float r = rs[ai * 4 + m];
;                 bf16_t* rowp = O + (size_t)row * ldc + col0;
; #pragma unroll
;                 for (int bj = 0; bj < 2; ++bj) { f32x4 v0 = acc[ai][bj][m][0] * r, v1 = acc[ai][bj][m][1] * r;
; #pragma unroll
;                     for (int e = 0; e < 4; ++e) { const float a = fmaxf(v0[e], 0.f), b = fmaxf(v1[e], 0.f); v0[e] = a * a; v1[e] = b * b; }
;                     *(u32x4*)(rowp + bj * HALF) = pack8(v0, v1); } }
	v_add_f32_e32 v176, v176, v177
	ds_bpermute_b32 v177, v175, v176
	v_add_u32_e32 v178, 0x40000, v172
	s_waitcnt lgkmcnt(0)
	v_add_f32_e32 v176, v176, v177
	v_fmamk_f32 v176, v176, 0x3a800000, v193
	v_rsq_f32_e32 v180, v176
	s_nop 0
	v_pk_mul_f32 v[92:93], v[92:93], v[180:181] op_sel_hi:[1,0]
	v_pk_mul_f32 v[94:95], v[94:95], v[180:181] op_sel_hi:[1,0]
	v_pk_mul_f32 v[88:89], v[88:89], v[180:181] op_sel_hi:[1,0]
	v_pk_mul_f32 v[90:91], v[90:91], v[180:181] op_sel_hi:[1,0]
	v_max_f32_e32 v92, 0, v92
	v_max_f32_e32 v93, 0, v93
	v_max_f32_e32 v94, 0, v94
	v_max_f32_e32 v95, 0, v95
	v_max_f32_e32 v88, 0, v88
	v_max_f32_e32 v89, 0, v89
	v_max_f32_e32 v90, 0, v90
	v_max_f32_e32 v91, 0, v91
	v_pk_mul_f32 v[92:93], v[92:93], v[92:93]
	v_pk_mul_f32 v[94:95], v[94:95], v[94:95]
	v_pk_mul_f32 v[88:89], v[88:89], v[88:89]
	v_pk_mul_f32 v[90:91], v[90:91], v[90:91]
	v_cvt_pk_bf16_f32 v92, v92, v93
	v_cvt_pk_bf16_f32 v93, v94, v95
	v_cvt_pk_bf16_f32 v94, v88, v89
	v_cvt_pk_bf16_f32 v95, v90, v91
	global_store_dwordx4 v178, v[92:95], s[0:1]
	v_pk_mul_f32 v[84:85], v[84:85], v[180:181] op_sel_hi:[1,0]
	v_pk_mul_f32 v[86:87], v[86:87], v[180:181] op_sel_hi:[1,0]
	v_pk_mul_f32 v[80:81], v[80:81], v[180:181] op_sel_hi:[1,0]
	v_pk_mul_f32 v[82:83], v[82:83], v[180:181] op_sel_hi:[1,0]
	v_max_f32_e32 v84, 0, v84
	v_max_f32_e32 v85, 0, v85
	v_max_f32_e32 v86, 0, v86
	v_max_f32_e32 v87, 0, v87
	v_max_f32_e32 v80, 0, v80
	v_max_f32_e32 v81, 0, v81
	v_max_f32_e32 v82, 0, v82
	v_max_f32_e32 v83, 0, v83
	v_pk_mul_f32 v[84:85], v[84:85], v[84:85]
	v_pk_mul_f32 v[86:87], v[86:87], v[86:87]
	v_pk_mul_f32 v[80:81], v[80:81], v[80:81]
	v_pk_mul_f32 v[82:83], v[82:83], v[82:83]
	v_cvt_pk_bf16_f32 v84, v84, v85
	v_cvt_pk_bf16_f32 v85, v86, v87
	v_cvt_pk_bf16_f32 v86, v80, v81
	v_cvt_pk_bf16_f32 v87, v82, v83
	global_store_dwordx4 v178, v[84:87], s[0:1] offset:256
	s_waitcnt vmcnt(10)
	v_add_f32_e32 v176, v140, v141
	v_add_f32_e32 v177, v142, v143
	v_add_f32_e32 v176, v176, v177
	ds_bpermute_b32 v177, v174, v176
	s_waitcnt lgkmcnt(0)
	v_add_f32_e32 v176, v176, v177
	ds_bpermute_b32 v177, v175, v176
	v_add_u32_e32 v178, 0x60000, v172
	s_waitcnt lgkmcnt(0)
	v_add_f32_e32 v176, v176, v177
	v_fmamk_f32 v176, v176, 0x3a800000, v193
	v_rsq_f32_e32 v180, v176
	s_nop 0
	v_pk_mul_f32 v[76:77], v[76:77], v[180:181] op_sel_hi:[1,0]
	v_pk_mul_f32 v[78:79], v[78:79], v[180:181] op_sel_hi:[1,0]
	v_pk_mul_f32 v[72:73], v[72:73], v[180:181] op_sel_hi:[1,0]
	v_pk_mul_f32 v[74:75], v[74:75], v[180:181] op_sel_hi:[1,0]
	v_max_f32_e32 v76, 0, v76
	v_max_f32_e32 v77, 0, v77
	v_max_f32_e32 v78, 0, v78
	v_max_f32_e32 v79, 0, v79
	v_max_f32_e32 v72, 0, v72
	v_max_f32_e32 v73, 0, v73
	v_max_f32_e32 v74, 0, v74
	v_max_f32_e32 v75, 0, v75
	v_pk_mul_f32 v[76:77], v[76:77], v[76:77]
	v_pk_mul_f32 v[78:79], v[78:79], v[78:79]
	v_pk_mul_f32 v[72:73], v[72:73], v[72:73]
	v_pk_mul_f32 v[74:75], v[74:75], v[74:75]
	v_cvt_pk_bf16_f32 v76, v76, v77
	v_cvt_pk_bf16_f32 v77, v78, v79
	v_cvt_pk_bf16_f32 v78, v72, v73
	v_cvt_pk_bf16_f32 v79, v74, v75
	global_store_dwordx4 v178, v[76:79], s[0:1]
	v_pk_mul_f32 v[68:69], v[68:69], v[180:181] op_sel_hi:[1,0]
	v_pk_mul_f32 v[70:71], v[70:71], v[180:181] op_sel_hi:[1,0]
	v_pk_mul_f32 v[64:65], v[64:65], v[180:181] op_sel_hi:[1,0]
	v_pk_mul_f32 v[66:67], v[66:67], v[180:181] op_sel_hi:[1,0]
	v_max_f32_e32 v68, 0, v68
	v_max_f32_e32 v69, 0, v69
	v_max_f32_e32 v70, 0, v70
	v_max_f32_e32 v71, 0, v71
	v_max_f32_e32 v64, 0, v64
	v_max_f32_e32 v65, 0, v65
	v_max_f32_e32 v66, 0, v66
	v_max_f32_e32 v67, 0, v67
	v_pk_mul_f32 v[68:69], v[68:69], v[68:69]
	v_pk_mul_f32 v[70:71], v[70:71], v[70:71]
	v_pk_mul_f32 v[64:65], v[64:65], v[64:65]
	v_pk_mul_f32 v[66:67], v[66:67], v[66:67]
	v_cvt_pk_bf16_f32 v68, v68, v69
	v_cvt_pk_bf16_f32 v69, v70, v71
	v_cvt_pk_bf16_f32 v70, v64, v65
	v_cvt_pk_bf16_f32 v71, v66, v67
	global_store_dwordx4 v178, v[68:71], s[0:1] offset:256
	s_waitcnt vmcnt(11)
	v_add_f32_e32 v176, v144, v145
	v_add_f32_e32 v177, v146, v147
	v_add_f32_e32 v176, v176, v177
	ds_bpermute_b32 v177, v174, v176
	s_waitcnt lgkmcnt(0)
	v_add_f32_e32 v176, v176, v177
	ds_bpermute_b32 v177, v175, v176
	v_add_u32_e32 v178, 0x100000, v172
	s_waitcnt lgkmcnt(0)
	v_add_f32_e32 v176, v176, v177
	v_fmamk_f32 v176, v176, 0x3a800000, v193
	v_rsq_f32_e32 v180, v176
	s_nop 0
	v_pk_mul_f32 v[60:61], v[60:61], v[180:181] op_sel_hi:[1,0]
	v_pk_mul_f32 v[62:63], v[62:63], v[180:181] op_sel_hi:[1,0]
	v_pk_mul_f32 v[56:57], v[56:57], v[180:181] op_sel_hi:[1,0]
	v_pk_mul_f32 v[58:59], v[58:59], v[180:181] op_sel_hi:[1,0]
	v_max_f32_e32 v60, 0, v60
	v_max_f32_e32 v61, 0, v61
	v_max_f32_e32 v62, 0, v62
	v_max_f32_e32 v63, 0, v63
	v_max_f32_e32 v56, 0, v56
	v_max_f32_e32 v57, 0, v57
	v_max_f32_e32 v58, 0, v58
	v_max_f32_e32 v59, 0, v59
	v_pk_mul_f32 v[60:61], v[60:61], v[60:61]
	v_pk_mul_f32 v[62:63], v[62:63], v[62:63]
	v_pk_mul_f32 v[56:57], v[56:57], v[56:57]
	v_pk_mul_f32 v[58:59], v[58:59], v[58:59]
	v_cvt_pk_bf16_f32 v60, v60, v61
	v_cvt_pk_bf16_f32 v61, v62, v63
	v_cvt_pk_bf16_f32 v62, v56, v57
	v_cvt_pk_bf16_f32 v63, v58, v59
	global_store_dwordx4 v178, v[60:63], s[0:1]
	v_pk_mul_f32 v[52:53], v[52:53], v[180:181] op_sel_hi:[1,0]
	v_pk_mul_f32 v[54:55], v[54:55], v[180:181] op_sel_hi:[1,0]
	v_pk_mul_f32 v[48:49], v[48:49], v[180:181] op_sel_hi:[1,0]
	v_pk_mul_f32 v[50:51], v[50:51], v[180:181] op_sel_hi:[1,0]
	v_max_f32_e32 v52, 0, v52
	v_max_f32_e32 v53, 0, v53
	v_max_f32_e32 v54, 0, v54
	v_max_f32_e32 v55, 0, v55
	v_max_f32_e32 v48, 0, v48
	v_max_f32_e32 v49, 0, v49
	v_max_f32_e32 v50, 0, v50
	v_max_f32_e32 v51, 0, v51
	v_pk_mul_f32 v[52:53], v[52:53], v[52:53]
	v_pk_mul_f32 v[54:55], v[54:55], v[54:55]
	v_pk_mul_f32 v[48:49], v[48:49], v[48:49]
	v_pk_mul_f32 v[50:51], v[50:51], v[50:51]
	v_cvt_pk_bf16_f32 v52, v52, v53
	v_cvt_pk_bf16_f32 v53, v54, v55
	v_cvt_pk_bf16_f32 v54, v48, v49
	v_cvt_pk_bf16_f32 v55, v50, v51
	global_store_dwordx4 v178, v[52:55], s[0:1] offset:256
	s_waitcnt vmcnt(12)
; __device__ __forceinline__ u32x4 pack8(const f32x4 v0, const f32x4 v1) { u32x4 w; w.x = cvt_pk_bf16(v0[0], v0[1]); w.y = cvt_pk_bf16(v0[2], v0[3]); w.z = cvt_pk_bf16(v1[0], v1[1]); w.w = cvt_pk_bf16(v1[2], v1[3]); return w; }
; __device__ __forceinline__ void row_rs8(float (&rs)[8], const float* ssq, int row0, int fq) {
;     ...
;     for (int i = 0; i < 8; ++i) p[i] = *(const f32x4*)(ssq + (size_t)(row0 + (i >> 2) * HALF + (i & 3) * 16) * 16 + 4 * fq);
; #pragma unroll
;     for (int i = 0; i < 8; ++i) { float s = (p[i][0] + p[i][1]) + (p[i][2] + p[i][3]); s += __shfl_xor(s, 16); s += __shfl_xor(s, 32); rs[i] = __builtin_amdgcn_rsqf(s * (1.0f / DMODEL) + RMS_EPS); }
;     __device__ __forceinline__ void operator()(const f32x4 (&acc)[2][2][4][2], const Unit& u, int wr, int wc, int fr, int fq) const {
;     ...
;             for (int m = 0; m < 4; ++m) { const int row = row0 + ai * HALF + m * 16; const float r = rs[ai * 4 + m];
;                 bf16_t* rowp = O + (size_t)row * ldc + col0;
; #pragma unroll
;                 for (int bj = 0; bj < 2; ++bj) { f32x4 v0 = acc[ai][bj][m][0] * r, v1 = acc[ai][bj][m][1] * r;
; #pragma unroll
;                     for (int e = 0; e < 4; ++e) { const float a = fmaxf(v0[e], 0.f), b = fmaxf(v1[e], 0.f); v0[e] = a * a; v1[e] = b * b; }
;                     *(u32x4*)(rowp + bj * HALF) = pack8(v0, v1); } }
	v_add_f32_e32 v176, v148, v149
	v_add_f32_e32 v177, v150, v151
	v_add_f32_e32 v176, v176, v177
	ds_bpermute_b32 v177, v174, v176
	s_waitcnt lgkmcnt(0)
	v_add_f32_e32 v176, v176, v177
	ds_bpermute_b32 v177, v175, v176
	v_add_u32_e32 v178, 0x120000, v172
	s_waitcnt lgkmcnt(0)
	v_add_f32_e32 v176, v176, v177
	v_fmamk_f32 v176, v176, 0x3a800000, v193
	v_rsq_f32_e32 v180, v176
	s_nop 0
	v_pk_mul_f32 v[44:45], v[44:45], v[180:181] op_sel_hi:[1,0]
	v_pk_mul_f32 v[46:47], v[46:47], v[180:181] op_sel_hi:[1,0]
	v_pk_mul_f32 v[40:41], v[40:41], v[180:181] op_sel_hi:[1,0]
	v_pk_mul_f32 v[42:43], v[42:43], v[180:181] op_sel_hi:[1,0]
	v_max_f32_e32 v44, 0, v44
	v_max_f32_e32 v45, 0, v45
	v_max_f32_e32 v46, 0, v46
	v_max_f32_e32 v47, 0, v47
	v_max_f32_e32 v40, 0, v40
	v_max_f32_e32 v41, 0, v41
	v_max_f32_e32 v42, 0, v42
	v_max_f32_e32 v43, 0, v43
	v_pk_mul_f32 v[44:45], v[44:45], v[44:45]
	v_pk_mul_f32 v[46:47], v[46:47], v[46:47]
	v_pk_mul_f32 v[40:41], v[40:41], v[40:41]
	v_pk_mul_f32 v[42:43], v[42:43], v[42:43]
	v_cvt_pk_bf16_f32 v44, v44, v45
	v_cvt_pk_bf16_f32 v45, v46, v47
	v_cvt_pk_bf16_f32 v46, v40, v41
	v_cvt_pk_bf16_f32 v47, v42, v43
	global_store_dwordx4 v178, v[44:47], s[0:1]
	v_pk_mul_f32 v[36:37], v[36:37], v[180:181] op_sel_hi:[1,0]
	v_pk_mul_f32 v[38:39], v[38:39], v[180:181] op_sel_hi:[1,0]
	v_pk_mul_f32 v[32:33], v[32:33], v[180:181] op_sel_hi:[1,0]
	v_pk_mul_f32 v[34:35], v[34:35], v[180:181] op_sel_hi:[1,0]
	v_max_f32_e32 v36, 0, v36
	v_max_f32_e32 v37, 0, v37
	v_max_f32_e32 v38, 0, v38
	v_max_f32_e32 v39, 0, v39
	v_max_f32_e32 v32, 0, v32
	v_max_f32_e32 v33, 0, v33
	v_max_f32_e32 v34, 0, v34
	v_max_f32_e32 v35, 0, v35
	v_pk_mul_f32 v[36:37], v[36:37], v[36:37]
	v_pk_mul_f32 v[38:39], v[38:39], v[38:39]
	v_pk_mul_f32 v[32:33], v[32:33], v[32:33]
	v_pk_mul_f32 v[34:35], v[34:35], v[34:35]
	v_cvt_pk_bf16_f32 v36, v36, v37
	v_cvt_pk_bf16_f32 v37, v38, v39
	v_cvt_pk_bf16_f32 v38, v32, v33
	v_cvt_pk_bf16_f32 v39, v34, v35
	global_store_dwordx4 v178, v[36:39], s[0:1] offset:256
	s_waitcnt vmcnt(13)
	v_add_f32_e32 v176, v164, v165
	v_add_f32_e32 v177, v166, v167
	v_add_f32_e32 v176, v176, v177
	ds_bpermute_b32 v177, v174, v176
	s_waitcnt lgkmcnt(0)
	v_add_f32_e32 v176, v176, v177
	ds_bpermute_b32 v177, v175, v176
	v_add_u32_e32 v178, 0x140000, v172
	s_waitcnt lgkmcnt(0)
	v_add_f32_e32 v176, v176, v177
	v_fmamk_f32 v176, v176, 0x3a800000, v193
	v_rsq_f32_e32 v180, v176
	s_nop 0
	v_pk_mul_f32 v[28:29], v[28:29], v[180:181] op_sel_hi:[1,0]
	v_pk_mul_f32 v[30:31], v[30:31], v[180:181] op_sel_hi:[1,0]
	v_pk_mul_f32 v[24:25], v[24:25], v[180:181] op_sel_hi:[1,0]
	v_pk_mul_f32 v[26:27], v[26:27], v[180:181] op_sel_hi:[1,0]
	v_max_f32_e32 v28, 0, v28
	v_max_f32_e32 v29, 0, v29
	v_max_f32_e32 v30, 0, v30
	v_max_f32_e32 v31, 0, v31
	v_max_f32_e32 v24, 0, v24
	v_max_f32_e32 v25, 0, v25
	v_max_f32_e32 v26, 0, v26
	v_max_f32_e32 v27, 0, v27
	v_pk_mul_f32 v[28:29], v[28:29], v[28:29]
	v_pk_mul_f32 v[30:31], v[30:31], v[30:31]
	v_pk_mul_f32 v[24:25], v[24:25], v[24:25]
	v_pk_mul_f32 v[26:27], v[26:27], v[26:27]
	v_cvt_pk_bf16_f32 v28, v28, v29
	v_cvt_pk_bf16_f32 v29, v30, v31
	v_cvt_pk_bf16_f32 v30, v24, v25
	v_cvt_pk_bf16_f32 v31, v26, v27
	global_store_dwordx4 v178, v[28:31], s[0:1]
	v_pk_mul_f32 v[20:21], v[20:21], v[180:181] op_sel_hi:[1,0]
	v_pk_mul_f32 v[22:23], v[22:23], v[180:181] op_sel_hi:[1,0]
	v_pk_mul_f32 v[16:17], v[16:17], v[180:181] op_sel_hi:[1,0]
	v_pk_mul_f32 v[18:19], v[18:19], v[180:181] op_sel_hi:[1,0]
	v_max_f32_e32 v20, 0, v20
	v_max_f32_e32 v21, 0, v21
	v_max_f32_e32 v22, 0, v22
	v_max_f32_e32 v23, 0, v23
	v_max_f32_e32 v16, 0, v16
	v_max_f32_e32 v17, 0, v17
	v_max_f32_e32 v18, 0, v18
	v_max_f32_e32 v19, 0, v19
	v_pk_mul_f32 v[20:21], v[20:21], v[20:21]
	v_pk_mul_f32 v[22:23], v[22:23], v[22:23]
	v_pk_mul_f32 v[16:17], v[16:17], v[16:17]
	v_pk_mul_f32 v[18:19], v[18:19], v[18:19]
	v_cvt_pk_bf16_f32 v20, v20, v21
	v_cvt_pk_bf16_f32 v21, v22, v23
	v_cvt_pk_bf16_f32 v22, v16, v17
	v_cvt_pk_bf16_f32 v23, v18, v19
	global_store_dwordx4 v178, v[20:23], s[0:1] offset:256
	s_waitcnt vmcnt(14)
	v_add_f32_e32 v176, v168, v169
	v_add_f32_e32 v177, v170, v171
	v_add_f32_e32 v176, v176, v177
	ds_bpermute_b32 v177, v174, v176
	s_waitcnt lgkmcnt(0)
	v_add_f32_e32 v176, v176, v177
	ds_bpermute_b32 v177, v175, v176
	v_add_u32_e32 v178, 0x160000, v172
	s_waitcnt lgkmcnt(0)
	v_add_f32_e32 v176, v176, v177
	v_fmamk_f32 v176, v176, 0x3a800000, v193
	v_rsq_f32_e32 v180, v176
	s_nop 0
	v_pk_mul_f32 v[12:13], v[12:13], v[180:181] op_sel_hi:[1,0]
	v_pk_mul_f32 v[14:15], v[14:15], v[180:181] op_sel_hi:[1,0]
	v_pk_mul_f32 v[8:9], v[8:9], v[180:181] op_sel_hi:[1,0]
	v_pk_mul_f32 v[10:11], v[10:11], v[180:181] op_sel_hi:[1,0]
	v_max_f32_e32 v12, 0, v12
	v_max_f32_e32 v13, 0, v13
	v_max_f32_e32 v14, 0, v14
	v_max_f32_e32 v15, 0, v15
	v_max_f32_e32 v8, 0, v8
	v_max_f32_e32 v9, 0, v9
	v_max_f32_e32 v10, 0, v10
	v_max_f32_e32 v11, 0, v11
	v_pk_mul_f32 v[12:13], v[12:13], v[12:13]
	v_pk_mul_f32 v[14:15], v[14:15], v[14:15]
	v_pk_mul_f32 v[8:9], v[8:9], v[8:9]
	v_pk_mul_f32 v[10:11], v[10:11], v[10:11]
	v_cvt_pk_bf16_f32 v12, v12, v13
	v_cvt_pk_bf16_f32 v13, v14, v15
	v_cvt_pk_bf16_f32 v14, v8, v9
	v_cvt_pk_bf16_f32 v15, v10, v11
	global_store_dwordx4 v178, v[12:15], s[0:1]
	v_pk_mul_f32 v[4:5], v[4:5], v[180:181] op_sel_hi:[1,0]
	v_pk_mul_f32 v[6:7], v[6:7], v[180:181] op_sel_hi:[1,0]
	v_pk_mul_f32 v[0:1], v[0:1], v[180:181] op_sel_hi:[1,0]
	v_pk_mul_f32 v[2:3], v[2:3], v[180:181] op_sel_hi:[1,0]
	v_max_f32_e32 v4, 0, v4
	v_max_f32_e32 v5, 0, v5
	v_max_f32_e32 v6, 0, v6
	v_max_f32_e32 v7, 0, v7
	v_max_f32_e32 v0, 0, v0
	v_max_f32_e32 v1, 0, v1
	v_max_f32_e32 v2, 0, v2
	v_max_f32_e32 v3, 0, v3
	v_pk_mul_f32 v[4:5], v[4:5], v[4:5]
	v_pk_mul_f32 v[6:7], v[6:7], v[6:7]
	v_pk_mul_f32 v[0:1], v[0:1], v[0:1]
	v_pk_mul_f32 v[2:3], v[2:3], v[2:3]
	v_cvt_pk_bf16_f32 v4, v4, v5
	v_cvt_pk_bf16_f32 v5, v6, v7
	v_cvt_pk_bf16_f32 v6, v0, v1
	v_cvt_pk_bf16_f32 v7, v2, v3
	global_store_dwordx4 v178, v[4:7], s[0:1] offset:256
	s_mov_b64 s[26:27], -1
	s_andn2_b64 vcc, exec, s[14:15]
	s_mov_b64 s[14:15], -1
	s_cbranch_vccnz .LBB0_601
	s_andn2_b64 vcc, exec, s[4:5]
	s_cbranch_vccnz .LBB0_600
	s_barrier
	s_branch .LBB0_600

; template <class Epi, class Sched, bool ALIGN_EPI = false, bool SP2 = false>
; __device__ __forceinline__ void gemm_phase(PG8_LAS unsigned char* lds, const Gemm g, const Sched& S, const Epi& E) {
;     ...
;         for (int a = 0; a < 2; ++a)
; #pragma unroll
;             for (int b = 0; b < 2; ++b)
; #pragma unroll
;                 for (int m = 0; m < 4; ++m)
; #pragma unroll
;                     for (int n = 0; n < 2; ++n) acc[a][b][m][n] = (f32x4){0.f, 0.f, 0.f, 0.f};
.LBB0_1089:
	v_mov_b32_e32 v123, 0
	s_andn2_b64 vcc, exec, s[14:15]
	v_mov_b32_e32 v122, v123
	v_mov_b32_e32 v121, v123
	v_mov_b32_e32 v120, v123
	v_mov_b32_e32 v127, v123
	v_mov_b32_e32 v126, v123
	v_mov_b32_e32 v125, v123
	v_mov_b32_e32 v124, v123
	v_mov_b32_e32 v111, v123
	v_mov_b32_e32 v110, v123
	v_mov_b32_e32 v109, v123
	v_mov_b32_e32 v108, v123
	v_mov_b32_e32 v107, v123
	v_mov_b32_e32 v106, v123
	v_mov_b32_e32 v105, v123
	v_mov_b32_e32 v104, v123
	v_mov_b32_e32 v95, v123
	v_mov_b32_e32 v94, v123
	v_mov_b32_e32 v93, v123
	v_mov_b32_e32 v92, v123
	v_mov_b32_e32 v91, v123
	v_mov_b32_e32 v90, v123
	v_mov_b32_e32 v89, v123
	v_mov_b32_e32 v88, v123
	v_mov_b32_e32 v79, v123
	v_mov_b32_e32 v78, v123
	v_mov_b32_e32 v77, v123
	v_mov_b32_e32 v76, v123
	v_mov_b32_e32 v75, v123
	v_mov_b32_e32 v74, v123
	v_mov_b32_e32 v73, v123
	v_mov_b32_e32 v72, v123
	v_mov_b32_e32 v119, v123
	v_mov_b32_e32 v118, v123
	v_mov_b32_e32 v117, v123
	v_mov_b32_e32 v116, v123
	v_mov_b32_e32 v115, v123
	v_mov_b32_e32 v114, v123
	v_mov_b32_e32 v113, v123
	v_mov_b32_e32 v112, v123
	v_mov_b32_e32 v103, v123
	v_mov_b32_e32 v102, v123
	v_mov_b32_e32 v101, v123
	v_mov_b32_e32 v100, v123
	v_mov_b32_e32 v99, v123
	v_mov_b32_e32 v98, v123
	v_mov_b32_e32 v97, v123
	v_mov_b32_e32 v96, v123
	v_mov_b32_e32 v87, v123
	v_mov_b32_e32 v86, v123
	v_mov_b32_e32 v85, v123
	v_mov_b32_e32 v84, v123
	v_mov_b32_e32 v83, v123
	v_mov_b32_e32 v82, v123
	v_mov_b32_e32 v81, v123
	v_mov_b32_e32 v80, v123
	v_mov_b32_e32 v71, v123
	v_mov_b32_e32 v70, v123
	v_mov_b32_e32 v69, v123
	v_mov_b32_e32 v68, v123
	v_mov_b32_e32 v67, v123
	v_mov_b32_e32 v66, v123
	v_mov_b32_e32 v65, v123
	v_mov_b32_e32 v64, v123
	v_mov_b32_e32 v63, v123
	v_mov_b32_e32 v62, v123
	v_mov_b32_e32 v61, v123
	v_mov_b32_e32 v60, v123
	v_mov_b32_e32 v59, v123
	v_mov_b32_e32 v58, v123
	v_mov_b32_e32 v57, v123
	v_mov_b32_e32 v56, v123
	v_mov_b32_e32 v47, v123
	v_mov_b32_e32 v46, v123
	v_mov_b32_e32 v45, v123
	v_mov_b32_e32 v44, v123
	v_mov_b32_e32 v43, v123
	v_mov_b32_e32 v42, v123
	v_mov_b32_e32 v41, v123
	v_mov_b32_e32 v40, v123
	v_mov_b32_e32 v31, v123
	v_mov_b32_e32 v30, v123
	v_mov_b32_e32 v29, v123
	v_mov_b32_e32 v28, v123
	v_mov_b32_e32 v27, v123
	v_mov_b32_e32 v26, v123
	v_mov_b32_e32 v25, v123
	v_mov_b32_e32 v24, v123
	v_mov_b32_e32 v15, v123
	v_mov_b32_e32 v14, v123
	v_mov_b32_e32 v13, v123
	v_mov_b32_e32 v12, v123
	v_mov_b32_e32 v11, v123
	v_mov_b32_e32 v10, v123
	v_mov_b32_e32 v9, v123
	v_mov_b32_e32 v8, v123
	v_mov_b32_e32 v55, v123
	v_mov_b32_e32 v54, v123
	v_mov_b32_e32 v53, v123
	v_mov_b32_e32 v52, v123
	v_mov_b32_e32 v51, v123
	v_mov_b32_e32 v50, v123
	v_mov_b32_e32 v49, v123
	v_mov_b32_e32 v48, v123
	v_mov_b32_e32 v39, v123
	v_mov_b32_e32 v38, v123
	v_mov_b32_e32 v37, v123
	v_mov_b32_e32 v36, v123
	v_mov_b32_e32 v35, v123
	v_mov_b32_e32 v34, v123
	v_mov_b32_e32 v33, v123
	v_mov_b32_e32 v32, v123
	v_mov_b32_e32 v23, v123
	v_mov_b32_e32 v22, v123
	v_mov_b32_e32 v21, v123
	v_mov_b32_e32 v20, v123
	v_mov_b32_e32 v19, v123
	v_mov_b32_e32 v18, v123
	v_mov_b32_e32 v17, v123
	v_mov_b32_e32 v16, v123
	v_mov_b32_e32 v7, v123
	v_mov_b32_e32 v6, v123
	v_mov_b32_e32 v5, v123
	v_mov_b32_e32 v4, v123
	v_mov_b32_e32 v3, v123
	v_mov_b32_e32 v2, v123
	v_mov_b32_e32 v1, v123
	v_mov_b32_e32 v0, v123
	s_cbranch_vccnz .LBB0_1092
	s_add_u32 s22, s22, 0x80
	s_addc_u32 s23, s23, 0
	s_add_u32 s60, s24, 0x100
	s_addc_u32 s61, s25, 0
	s_mov_b32 s24, 0
	v_mov_b64_e32 v[0:1], 0
	v_mov_b64_e32 v[2:3], 0
	v_mov_b64_e32 v[4:5], 0
	v_mov_b64_e32 v[6:7], 0
	v_mov_b64_e32 v[8:9], 0
	v_mov_b64_e32 v[10:11], 0
	v_mov_b64_e32 v[12:13], 0
	v_mov_b64_e32 v[14:15], 0
	v_mov_b64_e32 v[16:17], 0
	v_mov_b64_e32 v[18:19], 0
	v_mov_b64_e32 v[20:21], 0
	v_mov_b64_e32 v[22:23], 0
	v_mov_b64_e32 v[24:25], 0
	v_mov_b64_e32 v[26:27], 0
	v_mov_b64_e32 v[28:29], 0
	v_mov_b64_e32 v[30:31], 0
	v_mov_b64_e32 v[32:33], 0
	v_mov_b64_e32 v[34:35], 0
	v_mov_b64_e32 v[36:37], 0
	v_mov_b64_e32 v[38:39], 0
	v_mov_b64_e32 v[40:41], 0
	v_mov_b64_e32 v[42:43], 0
	v_mov_b64_e32 v[44:45], 0
	v_mov_b64_e32 v[46:47], 0
	v_mov_b64_e32 v[48:49], 0
	v_mov_b64_e32 v[50:51], 0
	v_mov_b64_e32 v[52:53], 0
	v_mov_b64_e32 v[54:55], 0
	v_mov_b64_e32 v[56:57], 0
	v_mov_b64_e32 v[58:59], 0
	v_mov_b64_e32 v[60:61], 0
	v_mov_b64_e32 v[62:63], 0
	v_mov_b64_e32 v[64:65], 0
	v_mov_b64_e32 v[66:67], 0
	v_mov_b64_e32 v[68:69], 0
	v_mov_b64_e32 v[70:71], 0
	v_mov_b64_e32 v[72:73], 0
	v_mov_b64_e32 v[74:75], 0
	v_mov_b64_e32 v[76:77], 0
	v_mov_b64_e32 v[78:79], 0
	v_mov_b64_e32 v[80:81], 0
	v_mov_b64_e32 v[82:83], 0
	v_mov_b64_e32 v[84:85], 0
	v_mov_b64_e32 v[86:87], 0
	v_mov_b64_e32 v[88:89], 0
	v_mov_b64_e32 v[90:91], 0
	v_mov_b64_e32 v[92:93], 0
	v_mov_b64_e32 v[94:95], 0
	v_mov_b64_e32 v[96:97], 0
	v_mov_b64_e32 v[98:99], 0
	v_mov_b64_e32 v[100:101], 0
	v_mov_b64_e32 v[102:103], 0
	v_mov_b64_e32 v[104:105], 0
	v_mov_b64_e32 v[106:107], 0
	v_mov_b64_e32 v[108:109], 0
	v_mov_b64_e32 v[110:111], 0
	v_mov_b64_e32 v[112:113], 0
	v_mov_b64_e32 v[114:115], 0
	v_mov_b64_e32 v[116:117], 0
	v_mov_b64_e32 v[118:119], 0
	v_mov_b64_e32 v[120:121], 0
	v_mov_b64_e32 v[122:123], 0
	v_mov_b64_e32 v[124:125], 0
	v_mov_b64_e32 v[126:127], 0

; template <class Epi, class Sched, bool ALIGN_EPI = false, bool SP2 = false>
; __device__ __forceinline__ void gemm_phase(PG8_LAS unsigned char* lds, const Gemm g, const Sched& S, const Epi& E) {
;     ...
;         const bool has_next = S.next(ui + 1, nxt);
;         const char* nA = has_next ? (const char*)g.A + (size_t)nxt.pm * tstep : cA; const char* nB = has_next ? (const char*)g.Bt + (size_t)nxt.pn * tstep : cB;
;         for (int t = 0; t < nt; t += 2) {
;             const bool last = (t == nt - 2);
;             const char* a1 = cA + (size_t)(t + 1) * kstep;
;             const char* a2 = last ? nA : cA + (size_t)(t + 2) * kstep; const char* b2 = last ? nB : cB + (size_t)(t + 2) * kstep;
;             const char* a3 = a2 + kstep; const char* b3 = b2 + kstep;
;     ...
;         for (int a = 0; a < 2; ++a)
; #pragma unroll
;             for (int b = 0; b < 2; ++b)
; #pragma unroll
;                 for (int m = 0; m < 4; ++m)
; #pragma unroll
;                     for (int n = 0; n < 2; ++n) acc[a][b][m][n] = (f32x4){0.f, 0.f, 0.f, 0.f};
.LBB0_1132:
	s_ashr_i32 s19, s18, 31
	s_lshl_b64 s[22:23], s[18:19], 19
	s_add_u32 s22, s6, s22
	s_addc_u32 s23, s7, s23
	s_and_b64 s[24:25], s[20:21], exec
	s_cselect_b32 s19, s23, s43
	s_cselect_b32 s27, s22, s42
	s_ashr_i32 s17, s16, 31
	s_lshl_b64 s[24:25], s[16:17], 19
	s_add_u32 s24, s44, s24
	s_addc_u32 s25, s46, s25
	s_and_b64 s[30:31], s[20:21], exec
	s_cselect_b32 s17, s25, s29
	s_cselect_b32 s34, s24, s28
	s_add_u32 s30, s42, 0x40080
	s_addc_u32 s31, s43, 0
	s_add_u32 s57, s28, 0x100
	v_lshl_add_u64 v[128:129], s[30:31], 0, v[156:157]
	v_lshl_add_u64 v[130:131], s[30:31], 0, v[158:159]
	s_addc_u32 s58, s29, 0
	s_mov_b32 s59, -2
	s_mov_b64 vcc, 0
	s_waitcnt lgkmcnt(0)
	v_mov_b64_e32 v[0:1], 0
	v_mov_b64_e32 v[2:3], 0
	v_mov_b64_e32 v[4:5], 0
	v_mov_b64_e32 v[6:7], 0
	v_mov_b64_e32 v[8:9], 0
	v_mov_b64_e32 v[10:11], 0
	v_mov_b64_e32 v[12:13], 0
	v_mov_b64_e32 v[14:15], 0
	v_mov_b64_e32 v[16:17], 0
	v_mov_b64_e32 v[18:19], 0
	v_mov_b64_e32 v[20:21], 0
	v_mov_b64_e32 v[22:23], 0
	v_mov_b64_e32 v[24:25], 0
	v_mov_b64_e32 v[26:27], 0
	v_mov_b64_e32 v[28:29], 0
	v_mov_b64_e32 v[30:31], 0
	v_mov_b64_e32 v[32:33], 0
	v_mov_b64_e32 v[34:35], 0
	v_mov_b64_e32 v[36:37], 0
	v_mov_b64_e32 v[38:39], 0
	v_mov_b64_e32 v[40:41], 0
	v_mov_b64_e32 v[42:43], 0
	v_mov_b64_e32 v[44:45], 0
	v_mov_b64_e32 v[46:47], 0
	v_mov_b64_e32 v[48:49], 0
	v_mov_b64_e32 v[50:51], 0
	v_mov_b64_e32 v[52:53], 0
	v_mov_b64_e32 v[54:55], 0
	v_mov_b64_e32 v[56:57], 0
	v_mov_b64_e32 v[58:59], 0
	v_mov_b64_e32 v[60:61], 0
	v_mov_b64_e32 v[62:63], 0
	v_mov_b64_e32 v[64:65], 0
	v_mov_b64_e32 v[66:67], 0
	v_mov_b64_e32 v[68:69], 0
	v_mov_b64_e32 v[70:71], 0
	v_mov_b64_e32 v[72:73], 0
	v_mov_b64_e32 v[74:75], 0
	v_mov_b64_e32 v[76:77], 0
	v_mov_b64_e32 v[78:79], 0
	v_mov_b64_e32 v[80:81], 0
	v_mov_b64_e32 v[82:83], 0
	v_mov_b64_e32 v[84:85], 0
	v_mov_b64_e32 v[86:87], 0
	v_mov_b64_e32 v[88:89], 0
	v_mov_b64_e32 v[90:91], 0
	v_mov_b64_e32 v[92:93], 0
	v_mov_b64_e32 v[94:95], 0
	v_mov_b64_e32 v[96:97], 0
	v_mov_b64_e32 v[98:99], 0
	v_mov_b64_e32 v[100:101], 0
	v_mov_b64_e32 v[102:103], 0
	v_mov_b64_e32 v[104:105], 0
	v_mov_b64_e32 v[106:107], 0
	v_mov_b64_e32 v[108:109], 0
	v_mov_b64_e32 v[110:111], 0
	v_mov_b64_e32 v[112:113], 0
	v_mov_b64_e32 v[114:115], 0
	v_mov_b64_e32 v[116:117], 0
	v_mov_b64_e32 v[118:119], 0
	v_mov_b64_e32 v[120:121], 0
	v_mov_b64_e32 v[122:123], 0
	v_mov_b64_e32 v[124:125], 0
	v_mov_b64_e32 v[126:127], 0
